# v60 + P3 scan gate recurrence lane-parallel: 16 lanes x one chunk (16-step row_shr DPP m-chain, same expf sequence per element) instead of one thread running 32 expf serially
# baseline (speedup 1.0000x reference)
.LBB0_951:
	s_or_b64 exec, exec, s[2:3]
	v_cmp_gt_u32_e32 vcc, 16, v84
	s_waitcnt lgkmcnt(0)
	s_barrier
	s_and_saveexec_b64 s[2:3], vcc
	s_cbranch_execz .LBB0_953
	v_lshlrev_b32_e32 v212, 3, v84
	ds_read_b64 v[214:215], v212 offset:256
	s_mov_b32 s1, 0x3fb8aa3b
	s_mov_b32 s4, 0xc2ce8ed0
	s_mov_b32 s5, 0x42b17218
	v_mov_b32_e32 v216, 0
	v_mov_b32_e32 v229, 0x7f800000
	v_lshlrev_b32_e32 v213, 2, v84
	s_waitcnt lgkmcnt(0)
	v_max_f32_e32 v217, v214, v214
	v_max_f32_e32 v218, v216, v217
	v_add_f32_e32 v219, v215, v218
	s_nop 1
	v_mov_b32_dpp v216, v219 row_shr:1 row_mask:0xf bank_mask:0xf bound_ctrl:1
	v_max_f32_e32 v218, v216, v217
	v_add_f32_e32 v219, v215, v218
	s_nop 1
	v_mov_b32_dpp v216, v219 row_shr:1 row_mask:0xf bank_mask:0xf bound_ctrl:1
	v_max_f32_e32 v218, v216, v217
	v_add_f32_e32 v219, v215, v218
	s_nop 1
	v_mov_b32_dpp v216, v219 row_shr:1 row_mask:0xf bank_mask:0xf bound_ctrl:1
	v_max_f32_e32 v218, v216, v217
	v_add_f32_e32 v219, v215, v218
	s_nop 1
	v_mov_b32_dpp v216, v219 row_shr:1 row_mask:0xf bank_mask:0xf bound_ctrl:1
	v_max_f32_e32 v218, v216, v217
	v_add_f32_e32 v219, v215, v218
	s_nop 1
	v_mov_b32_dpp v216, v219 row_shr:1 row_mask:0xf bank_mask:0xf bound_ctrl:1
	v_max_f32_e32 v218, v216, v217
	v_add_f32_e32 v219, v215, v218
	s_nop 1
	v_mov_b32_dpp v216, v219 row_shr:1 row_mask:0xf bank_mask:0xf bound_ctrl:1
	v_max_f32_e32 v218, v216, v217
	v_add_f32_e32 v219, v215, v218
	s_nop 1
	v_mov_b32_dpp v216, v219 row_shr:1 row_mask:0xf bank_mask:0xf bound_ctrl:1
	v_max_f32_e32 v218, v216, v217
	v_add_f32_e32 v219, v215, v218
	s_nop 1
	v_mov_b32_dpp v216, v219 row_shr:1 row_mask:0xf bank_mask:0xf bound_ctrl:1
	v_max_f32_e32 v218, v216, v217
	v_add_f32_e32 v219, v215, v218
	s_nop 1
	v_mov_b32_dpp v216, v219 row_shr:1 row_mask:0xf bank_mask:0xf bound_ctrl:1
	v_max_f32_e32 v218, v216, v217
	v_add_f32_e32 v219, v215, v218
	s_nop 1
	v_mov_b32_dpp v216, v219 row_shr:1 row_mask:0xf bank_mask:0xf bound_ctrl:1
	v_max_f32_e32 v218, v216, v217
	v_add_f32_e32 v219, v215, v218
	s_nop 1
	v_mov_b32_dpp v216, v219 row_shr:1 row_mask:0xf bank_mask:0xf bound_ctrl:1
	v_max_f32_e32 v218, v216, v217
	v_add_f32_e32 v219, v215, v218
	s_nop 1
	v_mov_b32_dpp v216, v219 row_shr:1 row_mask:0xf bank_mask:0xf bound_ctrl:1
	v_max_f32_e32 v218, v216, v217
	v_add_f32_e32 v219, v215, v218
	s_nop 1
	v_mov_b32_dpp v216, v219 row_shr:1 row_mask:0xf bank_mask:0xf bound_ctrl:1
	v_max_f32_e32 v218, v216, v217
	v_add_f32_e32 v219, v215, v218
	s_nop 1
	v_mov_b32_dpp v216, v219 row_shr:1 row_mask:0xf bank_mask:0xf bound_ctrl:1
	v_max_f32_e32 v218, v216, v217
	v_add_f32_e32 v219, v215, v218
	s_nop 1
	v_mov_b32_dpp v216, v219 row_shr:1 row_mask:0xf bank_mask:0xf bound_ctrl:1
	v_max_f32_e32 v218, v216, v217
	v_add_f32_e32 v219, v215, v218
	s_nop 1
	v_mov_b32_dpp v216, v219 row_shr:1 row_mask:0xf bank_mask:0xf bound_ctrl:1
	v_add_f32_e32 v220, v216, v215
	v_add_f32_e32 v221, v214, v215
	v_sub_f32_e32 v220, v220, v219
	v_sub_f32_e32 v221, v221, v219
	v_mul_f32_e32 v222, 0x3fb8aa3b, v220
	v_mul_f32_e32 v223, 0x3fb8aa3b, v221
	v_fma_f32 v224, v220, s1, -v222
	v_fma_f32 v225, v221, s1, -v223
	v_rndne_f32_e32 v226, v222
	v_rndne_f32_e32 v227, v223
	v_fmac_f32_e32 v224, 0x32a5705f, v220
	v_fmac_f32_e32 v225, 0x32a5705f, v221
	v_sub_f32_e32 v222, v222, v226
	v_sub_f32_e32 v223, v223, v227
	v_add_f32_e32 v222, v222, v224
	v_add_f32_e32 v223, v223, v225
	v_exp_f32_e32 v222, v222
	v_exp_f32_e32 v223, v223
	v_cvt_i32_f32_e32 v226, v226
	v_cvt_i32_f32_e32 v227, v227
	v_ldexp_f32 v222, v222, v226
	v_ldexp_f32 v223, v223, v227
	v_cmp_ngt_f32_e32 vcc, s4, v220
	s_nop 1
	v_cndmask_b32_e32 v222, 0, v222, vcc
	v_cmp_nlt_f32_e32 vcc, s5, v220
	s_nop 1
	v_cndmask_b32_e32 v222, v229, v222, vcc
	v_cmp_ngt_f32_e32 vcc, s4, v221
	s_nop 1
	v_cndmask_b32_e32 v223, 0, v223, vcc
	v_cmp_nlt_f32_e32 vcc, s5, v221
	s_nop 1
	v_cndmask_b32_e32 v223, v229, v223, vcc
	v_mov_b32_e32 v224, 0
	ds_write_b32 v213, v222
	ds_write_b32 v213, v223 offset:64
	ds_write_b32 v213, v219 offset:132
	ds_write_b32 v224, v224 offset:128
